# tail GEMM partial tiles stored write-through (sc0 sc1) so the tail barrier needs no L2 writeback; on top of the pipelined main row phase
# baseline (speedup 1.0000x reference)
; __device__ __forceinline__ unsigned cvt_pk_bf16(float lo, float hi) { unsigned r; asm volatile("v_cvt_pk_bf16_f32 %0, %1, %2" : "=v"(r) : "v"(lo), "v"(hi)); return r; }
;     __device__ __forceinline__ void operator()(const f32x4 (&acc)[2][2][4][2], const Unit& u, int wr, int wc, int fr_, int fq_) const {
;     ...
;             for (int m = 0; m < 4; ++m) { bf16_t* rowp = O + (size_t)(row0 + ai * HALF + m * 16) * ldc + col0; float sc = 1.0f;
;                 if (rsdiv > 0.f) { const float* pp = rs + (size_t)(row0 + ai * HALF + m * 16) * 20 + 12; const f32x4 pa = *(const f32x4*)pp, pb = *(const f32x4*)(pp + 4);
;                     sc = 1.0f / sqrtf((((pa[0] + pa[1]) + (pa[2] + pa[3])) + ((pb[0] + pb[1]) + (pb[2] + pb[3]))) / rsdiv + 1e-6f); }
;                 else if (rs) sc = rs[row0 + ai * HALF + m * 16];
; #pragma unroll
;                 for (int bj = 0; bj < 2; ++bj) { const f32x4 v0 = acc[ai][bj][m][0] * sc, v1 = acc[ai][bj][m][1] * sc;
;                     u32x4 w; w.x = cvt_pk_bf16(v0[0], v0[1]); w.y = cvt_pk_bf16(v0[2], v0[3]); w.z = cvt_pk_bf16(v1[0], v1[1]); w.w = cvt_pk_bf16(v1[2], v1[3]);
;                     *(u32x4*)(rowp + bj * HALF) = w; } }
.LBB0_834:
	s_lshl_b32 s0, s1, 5
	v_ashrrev_i32_e32 v130, 1, v130
	v_readlane_b32 s1, v255, 12
	v_and_b32_e32 v130, -8, v130
	s_or_b32 s0, s0, s1
	v_add_u32_e32 v130, s0, v130
	v_lshlrev_b64 v[138:139], 11, v[132:133]
	v_ashrrev_i32_e32 v131, 31, v130
	v_lshl_add_u64 v[138:139], s[4:5], 0, v[138:139]
	v_lshl_add_u64 v[138:139], v[130:131], 1, v[138:139]
	s_waitcnt vmcnt(0)
	v_pk_mul_f32 v[128:129], v[128:129], v[136:137] op_sel_hi:[1,0]
	v_pk_mul_f32 v[126:127], v[126:127], v[136:137] op_sel_hi:[1,0]
	v_pk_mul_f32 v[140:141], v[124:125], v[136:137] op_sel_hi:[1,0]
	v_pk_mul_f32 v[124:125], v[122:123], v[136:137] op_sel_hi:[1,0]
	v_cvt_pk_bf16_f32 v122, v126, v127
	v_cvt_pk_bf16_f32 v123, v128, v129
	v_pk_mul_f32 v[120:121], v[120:121], v[136:137] op_sel_hi:[1,0]
	v_cvt_pk_bf16_f32 v124, v124, v125
	v_cvt_pk_bf16_f32 v125, v140, v141
	global_store_dwordx4 v[138:139], v[122:125], off sc0 sc1
	v_pk_mul_f32 v[118:119], v[118:119], v[136:137] op_sel_hi:[1,0]
	s_xor_b64 s[0:1], s[10:11], -1
	v_pk_mul_f32 v[122:123], v[116:117], v[136:137] op_sel_hi:[1,0]
	v_pk_mul_f32 v[116:117], v[114:115], v[136:137] op_sel_hi:[1,0]
	v_cvt_pk_bf16_f32 v114, v118, v119
	v_cvt_pk_bf16_f32 v115, v120, v121
	s_andn2_b64 vcc, exec, s[0:1]
	v_cvt_pk_bf16_f32 v116, v116, v117
	v_cvt_pk_bf16_f32 v117, v122, v123
	global_store_dwordx4 v[138:139], v[114:117], off offset:256 sc0 sc1
	s_nop 1
	v_or_b32_e32 v114, 16, v132
	v_cndmask_b32_e64 v115, 0, 1, s[0:1]
	v_cmp_ne_u32_e64 s[2:3], 1, v115
	v_ashrrev_i32_e32 v115, 31, v114
	s_cbranch_vccnz .LBB0_836
	v_lshl_add_u64 v[116:117], v[114:115], 2, s[8:9]
	global_load_dword v134, v[116:117], off
.LBB0_836:
	v_lshlrev_b64 v[114:115], 11, v[114:115]
	v_lshl_add_u64 v[114:115], s[4:5], 0, v[114:115]
	v_lshl_add_u64 v[114:115], v[130:131], 1, v[114:115]
	s_waitcnt vmcnt(0)
	v_pk_mul_f32 v[112:113], v[112:113], v[134:135] op_sel_hi:[1,0]
	v_pk_mul_f32 v[110:111], v[110:111], v[134:135] op_sel_hi:[1,0]
	v_pk_mul_f32 v[116:117], v[108:109], v[134:135] op_sel_hi:[1,0]
	v_pk_mul_f32 v[108:109], v[106:107], v[134:135] op_sel_hi:[1,0]
	v_cvt_pk_bf16_f32 v106, v110, v111
	v_cvt_pk_bf16_f32 v107, v112, v113
	v_pk_mul_f32 v[102:103], v[102:103], v[134:135] op_sel_hi:[1,0]
	v_cvt_pk_bf16_f32 v108, v108, v109
	v_cvt_pk_bf16_f32 v109, v116, v117
	global_store_dwordx4 v[114:115], v[106:109], off sc0 sc1
	v_pk_mul_f32 v[104:105], v[104:105], v[134:135] op_sel_hi:[1,0]
	s_and_b64 vcc, exec, s[2:3]
	v_pk_mul_f32 v[106:107], v[100:101], v[134:135] op_sel_hi:[1,0]
	v_pk_mul_f32 v[100:101], v[98:99], v[134:135] op_sel_hi:[1,0]
	v_cvt_pk_bf16_f32 v98, v102, v103
	v_cvt_pk_bf16_f32 v99, v104, v105
	v_or_b32_e32 v102, 32, v132
	v_cvt_pk_bf16_f32 v100, v100, v101
	v_cvt_pk_bf16_f32 v101, v106, v107
	global_store_dwordx4 v[114:115], v[98:101], off offset:256 sc0 sc1
	v_ashrrev_i32_e32 v103, 31, v102
	s_movk_i32 s84, 0xf7f0
	v_mov_b32_e32 v98, 1.0
	v_mov_b32_e32 v100, 1.0
	s_cbranch_vccnz .LBB0_838
	v_lshl_add_u64 v[100:101], v[102:103], 2, s[8:9]
	global_load_dword v100, v[100:101], off
.LBB0_838:
	v_lshlrev_b64 v[102:103], 11, v[102:103]
	v_lshl_add_u64 v[102:103], s[4:5], 0, v[102:103]
	v_lshl_add_u64 v[102:103], v[130:131], 1, v[102:103]
	s_waitcnt vmcnt(0)
	v_pk_mul_f32 v[96:97], v[96:97], v[100:101] op_sel_hi:[1,0]
	v_pk_mul_f32 v[94:95], v[94:95], v[100:101] op_sel_hi:[1,0]
	v_pk_mul_f32 v[104:105], v[92:93], v[100:101] op_sel_hi:[1,0]
	v_pk_mul_f32 v[92:93], v[90:91], v[100:101] op_sel_hi:[1,0]
	v_cvt_pk_bf16_f32 v90, v94, v95
	v_cvt_pk_bf16_f32 v91, v96, v97
	v_pk_mul_f32 v[86:87], v[86:87], v[100:101] op_sel_hi:[1,0]
	v_cvt_pk_bf16_f32 v92, v92, v93
	v_cvt_pk_bf16_f32 v93, v104, v105
	global_store_dwordx4 v[102:103], v[90:93], off sc0 sc1
	v_pk_mul_f32 v[88:89], v[88:89], v[100:101] op_sel_hi:[1,0]
	s_and_b64 vcc, exec, s[2:3]
	v_pk_mul_f32 v[90:91], v[84:85], v[100:101] op_sel_hi:[1,0]
	v_pk_mul_f32 v[84:85], v[82:83], v[100:101] op_sel_hi:[1,0]
	v_cvt_pk_bf16_f32 v82, v86, v87
	v_cvt_pk_bf16_f32 v83, v88, v89
	s_nop 0
	v_cvt_pk_bf16_f32 v84, v84, v85
	v_cvt_pk_bf16_f32 v85, v90, v91
	global_store_dwordx4 v[102:103], v[82:85], off offset:256 sc0 sc1
	s_nop 1
	v_or_b32_e32 v82, 48, v132
	v_ashrrev_i32_e32 v83, 31, v82
	s_cbranch_vccnz .LBB0_840
	v_lshl_add_u64 v[84:85], v[82:83], 2, s[8:9]
	global_load_dword v98, v[84:85], off
.LBB0_840:
	v_lshlrev_b64 v[82:83], 11, v[82:83]
	v_lshl_add_u64 v[82:83], s[4:5], 0, v[82:83]
	v_lshl_add_u64 v[82:83], v[130:131], 1, v[82:83]
	s_waitcnt vmcnt(0)
	v_pk_mul_f32 v[80:81], v[80:81], v[98:99] op_sel_hi:[1,0]
	v_pk_mul_f32 v[78:79], v[78:79], v[98:99] op_sel_hi:[1,0]
	v_pk_mul_f32 v[84:85], v[76:77], v[98:99] op_sel_hi:[1,0]
	v_pk_mul_f32 v[76:77], v[74:75], v[98:99] op_sel_hi:[1,0]
	v_cvt_pk_bf16_f32 v74, v78, v79
	v_cvt_pk_bf16_f32 v75, v80, v81
	v_pk_mul_f32 v[70:71], v[70:71], v[98:99] op_sel_hi:[1,0]
	v_cvt_pk_bf16_f32 v76, v76, v77
	v_cvt_pk_bf16_f32 v77, v84, v85
	global_store_dwordx4 v[82:83], v[74:77], off sc0 sc1
	v_pk_mul_f32 v[72:73], v[72:73], v[98:99] op_sel_hi:[1,0]
	s_and_b64 vcc, exec, s[2:3]
	v_pk_mul_f32 v[74:75], v[68:69], v[98:99] op_sel_hi:[1,0]
	v_pk_mul_f32 v[68:69], v[66:67], v[98:99] op_sel_hi:[1,0]
	v_cvt_pk_bf16_f32 v66, v70, v71
	v_cvt_pk_bf16_f32 v67, v72, v73
	v_add_u32_e32 v70, 0x8080, v1
	v_cvt_pk_bf16_f32 v68, v68, v69
	v_cvt_pk_bf16_f32 v69, v74, v75
	global_store_dwordx4 v[82:83], v[66:69], off offset:256 sc0 sc1
	v_ashrrev_i32_e32 v71, 31, v70
	s_nop 0
	v_mov_b32_e32 v66, 1.0
	v_mov_b32_e32 v68, 1.0
	s_cbranch_vccnz .LBB0_842
	v_lshl_add_u64 v[68:69], v[70:71], 2, s[8:9]
	global_load_dword v68, v[68:69], off
; __device__ __forceinline__ unsigned cvt_pk_bf16(float lo, float hi) { unsigned r; asm volatile("v_cvt_pk_bf16_f32 %0, %1, %2" : "=v"(r) : "v"(lo), "v"(hi)); return r; }
; __device__ __forceinline__ unsigned xb_add(unsigned* p, unsigned v) { return __hip_atomic_fetch_add(p, v, __ATOMIC_RELAXED, __HIP_MEMORY_SCOPE_AGENT); }
;     __device__ __forceinline__ void operator()(const f32x4 (&acc)[2][2][4][2], const Unit& u, int wr, int wc, int fr_, int fq_) const {
;     ...
;             for (int m = 0; m < 4; ++m) { bf16_t* rowp = O + (size_t)(row0 + ai * HALF + m * 16) * ldc + col0; float sc = 1.0f;
;                 if (rsdiv > 0.f) { const float* pp = rs + (size_t)(row0 + ai * HALF + m * 16) * 20 + 12; const f32x4 pa = *(const f32x4*)pp, pb = *(const f32x4*)(pp + 4);
;                     sc = 1.0f / sqrtf((((pa[0] + pa[1]) + (pa[2] + pa[3])) + ((pb[0] + pb[1]) + (pb[2] + pb[3]))) / rsdiv + 1e-6f); }
;                 else if (rs) sc = rs[row0 + ai * HALF + m * 16];
; #pragma unroll
;                 for (int bj = 0; bj < 2; ++bj) { const f32x4 v0 = acc[ai][bj][m][0] * sc, v1 = acc[ai][bj][m][1] * sc;
;                     u32x4 w; w.x = cvt_pk_bf16(v0[0], v0[1]); w.y = cvt_pk_bf16(v0[2], v0[3]); w.z = cvt_pk_bf16(v1[0], v1[1]); w.w = cvt_pk_bf16(v1[2], v1[3]);
;                     *(u32x4*)(rowp + bj * HALF) = w; } }
; __device__ __forceinline__ void tail_barrier(unsigned* ctr, int tid, unsigned nwg) {
;     asm volatile("s_waitcnt vmcnt(0)" ::: "memory");
;     __syncthreads();
;     if (tid == 0) {
;         __builtin_amdgcn_fence(__ATOMIC_RELEASE, "agent");
;         asm volatile("s_waitcnt vmcnt(0)" ::: "memory");
;         (void)xb_add(ctr, 1u);
.LBB0_842:
	v_lshlrev_b64 v[70:71], 11, v[70:71]
	v_lshl_add_u64 v[70:71], s[4:5], 0, v[70:71]
	v_lshl_add_u64 v[70:71], v[130:131], 1, v[70:71]
	s_waitcnt vmcnt(0)
	v_pk_mul_f32 v[64:65], v[64:65], v[68:69] op_sel_hi:[1,0]
	v_pk_mul_f32 v[62:63], v[62:63], v[68:69] op_sel_hi:[1,0]
	v_pk_mul_f32 v[72:73], v[60:61], v[68:69] op_sel_hi:[1,0]
	v_pk_mul_f32 v[60:61], v[58:59], v[68:69] op_sel_hi:[1,0]
	v_cvt_pk_bf16_f32 v58, v62, v63
	v_cvt_pk_bf16_f32 v59, v64, v65
	v_pk_mul_f32 v[54:55], v[54:55], v[68:69] op_sel_hi:[1,0]
	v_cvt_pk_bf16_f32 v60, v60, v61
	v_cvt_pk_bf16_f32 v61, v72, v73
	global_store_dwordx4 v[70:71], v[58:61], off sc0 sc1
	v_pk_mul_f32 v[56:57], v[56:57], v[68:69] op_sel_hi:[1,0]
	s_and_b64 vcc, exec, s[2:3]
	v_pk_mul_f32 v[58:59], v[52:53], v[68:69] op_sel_hi:[1,0]
	v_pk_mul_f32 v[52:53], v[50:51], v[68:69] op_sel_hi:[1,0]
	v_cvt_pk_bf16_f32 v50, v54, v55
	v_cvt_pk_bf16_f32 v51, v56, v57
	s_nop 0
	v_cvt_pk_bf16_f32 v52, v52, v53
	v_cvt_pk_bf16_f32 v53, v58, v59
	global_store_dwordx4 v[70:71], v[50:53], off offset:256 sc0 sc1
	s_nop 1
	v_add_u32_e32 v50, 0x8090, v1
	v_ashrrev_i32_e32 v51, 31, v50
	s_cbranch_vccnz .LBB0_844
	v_lshl_add_u64 v[52:53], v[50:51], 2, s[8:9]
	global_load_dword v66, v[52:53], off
.LBB0_844:
	v_lshlrev_b64 v[50:51], 11, v[50:51]
	v_lshl_add_u64 v[50:51], s[4:5], 0, v[50:51]
	v_lshl_add_u64 v[50:51], v[130:131], 1, v[50:51]
	s_waitcnt vmcnt(0)
	v_pk_mul_f32 v[48:49], v[48:49], v[66:67] op_sel_hi:[1,0]
	v_pk_mul_f32 v[46:47], v[46:47], v[66:67] op_sel_hi:[1,0]
	v_pk_mul_f32 v[52:53], v[44:45], v[66:67] op_sel_hi:[1,0]
	v_pk_mul_f32 v[44:45], v[42:43], v[66:67] op_sel_hi:[1,0]
	v_cvt_pk_bf16_f32 v42, v46, v47
	v_cvt_pk_bf16_f32 v43, v48, v49
	v_pk_mul_f32 v[38:39], v[38:39], v[66:67] op_sel_hi:[1,0]
	v_cvt_pk_bf16_f32 v44, v44, v45
	v_cvt_pk_bf16_f32 v45, v52, v53
	global_store_dwordx4 v[50:51], v[42:45], off sc0 sc1
	v_pk_mul_f32 v[40:41], v[40:41], v[66:67] op_sel_hi:[1,0]
	s_and_b64 vcc, exec, s[2:3]
	v_pk_mul_f32 v[42:43], v[36:37], v[66:67] op_sel_hi:[1,0]
	v_pk_mul_f32 v[36:37], v[34:35], v[66:67] op_sel_hi:[1,0]
	v_cvt_pk_bf16_f32 v34, v38, v39
	v_cvt_pk_bf16_f32 v35, v40, v41
	v_add_u32_e32 v38, 0x80a0, v1
	v_cvt_pk_bf16_f32 v36, v36, v37
	v_cvt_pk_bf16_f32 v37, v42, v43
	global_store_dwordx4 v[50:51], v[34:37], off offset:256 sc0 sc1
	v_ashrrev_i32_e32 v39, 31, v38
	s_nop 0
	v_mov_b32_e32 v34, 1.0
	v_mov_b32_e32 v36, 1.0
	s_cbranch_vccnz .LBB0_846
	v_lshl_add_u64 v[36:37], v[38:39], 2, s[8:9]
	global_load_dword v36, v[36:37], off
.LBB0_846:
	v_lshlrev_b64 v[38:39], 11, v[38:39]
	v_lshl_add_u64 v[38:39], s[4:5], 0, v[38:39]
	v_lshl_add_u64 v[38:39], v[130:131], 1, v[38:39]
	s_waitcnt vmcnt(0)
	v_pk_mul_f32 v[32:33], v[32:33], v[36:37] op_sel_hi:[1,0]
	v_pk_mul_f32 v[30:31], v[30:31], v[36:37] op_sel_hi:[1,0]
	v_pk_mul_f32 v[40:41], v[28:29], v[36:37] op_sel_hi:[1,0]
	v_pk_mul_f32 v[28:29], v[26:27], v[36:37] op_sel_hi:[1,0]
	v_cvt_pk_bf16_f32 v26, v30, v31
	v_cvt_pk_bf16_f32 v27, v32, v33
	v_pk_mul_f32 v[22:23], v[22:23], v[36:37] op_sel_hi:[1,0]
	v_cvt_pk_bf16_f32 v28, v28, v29
	v_cvt_pk_bf16_f32 v29, v40, v41
	global_store_dwordx4 v[38:39], v[26:29], off sc0 sc1
	v_pk_mul_f32 v[24:25], v[24:25], v[36:37] op_sel_hi:[1,0]
	s_and_b64 vcc, exec, s[2:3]
	v_pk_mul_f32 v[26:27], v[20:21], v[36:37] op_sel_hi:[1,0]
	v_pk_mul_f32 v[20:21], v[18:19], v[36:37] op_sel_hi:[1,0]
	v_cvt_pk_bf16_f32 v18, v22, v23
	v_cvt_pk_bf16_f32 v19, v24, v25
	s_nop 0
	v_cvt_pk_bf16_f32 v20, v20, v21
	v_cvt_pk_bf16_f32 v21, v26, v27
	global_store_dwordx4 v[38:39], v[18:21], off offset:256 sc0 sc1
	s_nop 1
	v_add_u32_e32 v18, 0x80b0, v1
	v_ashrrev_i32_e32 v19, 31, v18
	s_cbranch_vccnz .LBB0_848
	v_lshl_add_u64 v[20:21], v[18:19], 2, s[8:9]
	global_load_dword v34, v[20:21], off
.LBB0_848:
	v_lshlrev_b64 v[18:19], 11, v[18:19]
	v_lshl_add_u64 v[18:19], s[4:5], 0, v[18:19]
	v_lshl_add_u64 v[18:19], v[130:131], 1, v[18:19]
	s_waitcnt vmcnt(0)
	v_pk_mul_f32 v[16:17], v[16:17], v[34:35] op_sel_hi:[1,0]
	v_pk_mul_f32 v[14:15], v[14:15], v[34:35] op_sel_hi:[1,0]
	v_pk_mul_f32 v[20:21], v[12:13], v[34:35] op_sel_hi:[1,0]
	v_pk_mul_f32 v[12:13], v[10:11], v[34:35] op_sel_hi:[1,0]
	v_cvt_pk_bf16_f32 v10, v14, v15
	v_cvt_pk_bf16_f32 v11, v16, v17
	v_pk_mul_f32 v[8:9], v[8:9], v[34:35] op_sel_hi:[1,0]
	v_cvt_pk_bf16_f32 v12, v12, v13
	v_cvt_pk_bf16_f32 v13, v20, v21
	global_store_dwordx4 v[18:19], v[10:13], off sc0 sc1
	v_pk_mul_f32 v[6:7], v[6:7], v[34:35] op_sel_hi:[1,0]
	s_mov_b64 s[4:5], s[88:89]
	v_pk_mul_f32 v[10:11], v[4:5], v[34:35] op_sel_hi:[1,0]
	v_pk_mul_f32 v[4:5], v[2:3], v[34:35] op_sel_hi:[1,0]
	v_cvt_pk_bf16_f32 v2, v6, v7
	v_cvt_pk_bf16_f32 v3, v8, v9
	v_readlane_b32 s0, v255, 0
	v_cvt_pk_bf16_f32 v4, v4, v5
	v_cvt_pk_bf16_f32 v5, v10, v11
	global_store_dwordx4 v[18:19], v[2:5], off offset:256 sc0 sc1
	s_waitcnt vmcnt(0)
	s_barrier
	v_mbcnt_lo_u32_b32 v1, -1, 0
	v_mbcnt_hi_u32_b32 v1, -1, v1
	s_waitcnt vmcnt(0)
	s_nop 0
	v_cmp_eq_u32_e32 vcc, s0, v1
	s_barrier
	s_and_saveexec_b64 s[2:3], vcc
	s_cbranch_execz .LBB0_860
	s_load_dwordx2 s[0:1], s[4:5], 0x98
	v_readlane_b32 s4, v255, 62
	v_readlane_b32 s5, v255, 60
	s_or_b32 s86, s5, s4
	s_lshl_b64 s[4:5], s[86:87], 2
	s_waitcnt lgkmcnt(0)
	s_add_u32 s0, s0, s4
	s_mov_b64 s[8:9], exec
	s_addc_u32 s1, s1, s5
	s_nop 0
	s_waitcnt vmcnt(0)
	s_waitcnt vmcnt(0)
	v_mbcnt_lo_u32_b32 v1, s8, 0
	s_add_u32 s4, s0, 0x3800
	v_mbcnt_hi_u32_b32 v1, s9, v1
	s_addc_u32 s5, s1, 0
	v_cmp_eq_u32_e32 vcc, 0, v1
	s_and_saveexec_b64 s[10:11], vcc
	s_cbranch_execz .LBB0_851
	s_bcnt1_i32_b64 s0, s[8:9]
	v_mov_b32_e32 v1, s0
	global_atomic_add v0, v1, s[4:5]
